# attention V^T LDS tile: row stride 144 B with key-permuted 16-key groups so each PV fragment is one aligned conflict-free ds_read_b128 instead of ds_read2_b64; bias LUT moved to 0x11800
# speedup vs baseline: 1.0123x; 1.0018x over previous
; #define LAS __attribute__((address_space(3)))
;     const int lane = tid & 63, r = lane & 31, hh = lane >> 5;
;     const int wave = __builtin_amdgcn_readfirstlane(tid >> 6), mi = wave & 1, g = wave >> 1;
;     const int w = bid, bh = w & 15, g16 = w >> 4, b = bh >> 3, h = bh & 7;
;     LAS float* lut = (LAS float*)(lds + AT_LUT); LAS float* ex = (LAS float*)lds;
;     const float NEG = -1e30f;
;     __syncthreads();
;     if (tid < 128) lut[tid] = lutg[h * 128 + tid] - rel_tab[31 * 8 + h] * LOG2E;
;     const bf16* kg = Kd + ((size_t)(b * SEQ)) * 1024 + h * 128 + (size_t)(tid >> 4) * 1024 + (tid & 15) * 8;
;     const bf16* vg = VTd + ((size_t)(bh * 128 + (tid >> 3))) * SEQ + (tid & 7) * 8;
;     const int kso = ((tid >> 4) * AT_KSTR + (tid & 15) * 8) * 2, vso = AT_VOFF + ((tid >> 3) * AT_VSTR + (tid & 7) * 8) * 2;
;     for (int ui = 0; ui < 4; ++ui) {
;         const int qb = ui == 0 ? g16 : (ui == 1 ? 31 - g16 : (ui == 2 ? 32 + g16 : 63 - g16));
;         const int qw = qb * 128 + 32 * g, NT = 2 * qb + 2, qabs = qw + r;
;         const bf16* qp = Qd + ((size_t)(b * SEQ + qabs)) * 1024 + h * 128 + 64 * mi + 8 * hh;
;         bf16x8_t qf[4];
; #pragma unroll
;         for (int ds = 0; ds < 4; ++ds) qf[ds] = *(const bf16x8_t*)(qp + 16 * ds);
;         f32x16 o[4];
; #pragma unroll
;         for (int dt = 0; dt < 4; ++dt)
; #pragma unroll
;             for (int i = 0; i < 16; ++i) o[dt][i] = 0.f;
;         float mref = 0.f, l = 0.f; bool first = true;
;         v4u kr0, kr1, vr0, vr1;
;         const int NTw = (qw + 31) / 64 + 1 < NT ? (qw + 31) / 64 + 1 : NT;
;         const bool isY = wave >= 4;
.LBB0_295:
	s_or_b64 exec, exec, s[28:29]
	s_lshl_b32 s24, s24, 7
	s_ashr_i32 s25, s24, 31
	s_lshl_b64 s[24:25], s[24:25], 2
	s_add_u32 s34, s40, s24
	s_addc_u32 s35, s41, s25
	s_ashr_i32 s26, s19, 6
	s_ashr_i32 s40, s19, 7
	s_lshl_b32 s19, s4, 10
	s_and_b32 s37, s19, 0x2000
	s_and_b32 s30, s26, 1
	s_and_b32 s24, s4, 15
	s_ashr_i32 s36, s4, 4
	s_lshl_b32 s19, s37, 11
	s_add_u32 s19, s6, s19
	v_ashrrev_i32_e32 v2, 4, v0
	s_addc_u32 s25, s7, 0
	s_lshl_b32 s27, s18, 1
	v_ashrrev_i32_e32 v3, 31, v2
	s_add_u32 s18, s19, s27
	v_lshlrev_b64 v[4:5], 11, v[2:3]
	v_lshlrev_b32_e32 v3, 3, v0
	s_addc_u32 s19, s25, 0
	v_and_b32_e32 v8, 0x78, v3
	v_lshl_add_u64 v[6:7], s[18:19], 0, v[4:5]
	v_lshlrev_b32_e32 v10, 1, v8
	v_mov_b32_e32 v11, v32
	v_ashrrev_i32_e32 v9, 3, v0
	v_lshl_add_u64 v[6:7], v[6:7], 0, v[10:11]
	v_lshl_add_u32 v10, s24, 7, v9
	v_ashrrev_i32_e32 v11, 31, v10
	v_lshlrev_b64 v[10:11], 14, v[10:11]
	v_and_b32_e32 v12, 56, v3
	s_mov_b64 s[18:19], 0x4300000
	v_lshl_add_u64 v[10:11], s[6:7], 0, v[10:11]
	v_lshlrev_b32_e32 v14, 1, v12
	v_mov_b32_e32 v15, v32
	v_lshl_add_u64 v[176:177], v[6:7], 0, s[18:19]
	v_lshl_add_u64 v[10:11], v[10:11], 0, v[14:15]
	s_mov_b64 s[18:19], 0x6300000
	s_movk_i32 s31, 0x88
	v_lshl_add_u64 v[178:179], v[10:11], 0, s[18:19]
	v_mad_u64_u32 v[2:3], s[18:19], v2, s31, v[8:9]
	s_movk_i32 s18, 0x48
	s_nop 0
	v_mad_u64_u32 v[8:9], s[18:19], v9, s18, v[12:13]
	s_lshl_b32 s42, s40, 5
	s_lshl_b32 s24, s30, 7
	s_add_u32 s18, s6, s27
	s_addc_u32 s19, s7, 0
	v_bfe_u32 v1, v0, 5, 1
	s_add_u32 s24, s18, s24
	s_addc_u32 s25, s19, 0
	v_lshlrev_b32_e32 v14, 4, v1
	v_lshl_add_u64 v[16:17], s[24:25], 0, v[14:15]
	s_mov_b64 s[24:25], 0x2300000
	s_cmp_gt_i32 s26, 3
	s_mov_b64 s[28:29], 0x4310000
	v_lshl_add_u64 v[180:181], v[16:17], 0, s[24:25]
	s_cselect_b64 s[24:25], -1, 0
	s_cmp_lt_i32 s26, 4
	v_lshl_add_u64 v[182:183], v[6:7], 0, s[28:29]
	s_mov_b64 s[28:29], 0x6400000
	s_cselect_b64 s[26:27], -1, 0
	v_lshl_add_u64 v[184:185], v[10:11], 0, s[28:29]
	s_mov_b64 s[28:29], 0x4320000
	s_sub_i32 s43, 31, s36
	s_add_i32 s44, s36, 32
	s_sub_i32 s45, 63, s36
	v_and_b32_e32 v218, 31, v0
	v_lshlrev_b32_e32 v12, 3, v1
	v_lshl_add_u64 v[186:187], v[6:7], 0, s[28:29]
	s_mov_b64 s[28:29], 0x4330000
	s_cmp_eq_u32 s30, 0
	v_lshl_add_u32 v219, v2, 1, 0
	v_lshl_add_u64 v[188:189], v[6:7], 0, s[28:29]
	v_mad_u32_u24 v2, v218, s31, v12
	s_cselect_b64 s[28:29], -1, 0
	s_cmp_eq_u32 s30, 1
	v_lshl_add_u32 v3, s30, 6, v2
	s_cselect_b64 s[30:31], -1, 0
	s_lshl_b32 s40, s40, 14
	v_mov_b32_e32 v13, v32
	v_lshl_add_u32 v221, v3, 1, 0
	v_add_u32_e32 v223, 0, v2
	v_lshl_add_u32 v223, v218, 3, v223
	v_lshl_add_u32 v223, v1, 3, v223
	s_add_i32 s40, s40, 0
	v_lshlrev_b32_e32 v2, 9, v1
	v_lshlrev_b32_e32 v3, 2, v218
	v_add3_u32 v224, s40, v2, v3
	v_lshl_add_u64 v[2:3], s[18:19], 0, v[12:13]
	s_mov_b64 s[18:19], 0xa300000
	v_lshl_add_u64 v[190:191], v[2:3], 0, s[18:19]
	v_not_b32_e32 v2, 16
	v_mad_i32_i24 v242, v1, -4, v2
	v_not_b32_e32 v2, 17
	v_mad_i32_i24 v243, v1, -4, v2
	v_not_b32_e32 v2, 18
	v_mad_i32_i24 v244, v1, -4, v2
	v_not_b32_e32 v2, 23
	v_mad_i32_i24 v245, v1, -4, v2
	v_not_b32_e32 v2, 24
	v_mad_i32_i24 v246, v1, -4, v2
	v_not_b32_e32 v2, 25
	s_lshl_b32 s4, s4, 21
	v_mad_i32_i24 v247, v1, -4, v2
	v_not_b32_e32 v2, 26
	s_and_b32 s94, s4, 0x1000000
	v_and_b32_e32 v0, 15, v0
	s_mov_b64 s[18:19], 0x4340000
	v_mad_i32_i24 v248, v1, -4, v2
	v_lshl_add_u64 v[2:3], s[94:95], 0, v[4:5]
	s_lshl_b32 s4, s5, 8
	v_lshlrev_b32_e32 v0, 4, v0
	v_lshl_add_u64 v[204:205], v[6:7], 0, s[18:19]
	s_mov_b64 s[18:19], 0x4350000
	v_or3_b32 v2, v2, s4, v0
	v_mul_i32_i24_e32 v222, -4, v1
	v_lshl_add_u64 v[206:207], v[6:7], 0, s[18:19]
	s_mov_b64 s[18:19], 0x6400080
	v_mad_i32_i24 v225, v1, -4, -1
	v_mad_i32_i24 v226, v1, -4, -2
	v_mad_i32_i24 v227, v1, -4, -3
	v_mad_i32_i24 v237, v1, -4, -8
	v_mad_i32_i24 v238, v1, -4, -9
	v_mad_i32_i24 v239, v1, -4, -10
	v_mad_i32_i24 v240, v1, -4, -11
	v_mad_i32_i24 v241, v1, -4, -16
	v_mad_i32_i24 v249, v1, -4, v218
	v_lshl_add_u64 v[0:1], s[6:7], 0, v[2:3]
	s_mov_b64 s[4:5], 0x4360000
	v_lshl_add_u32 v220, v8, 1, 0
	v_and_b32_e32 v230, 1, v228
	v_lshlrev_b32_e32 v230, 3, v230
	v_sub_u32_e32 v220, v220, v230
	s_mov_b32 s46, 0
	v_lshl_add_u64 v[192:193], s[34:35], 0, v[14:15]
	v_lshl_add_u64 v[208:209], v[10:11], 0, s[18:19]
	v_lshl_add_u64 v[210:211], v[0:1], 0, s[4:5]
	s_branch .LBB0_297

; #define AT_LOADK(t) do { kr0 = *(const v4u*)(kg + (size_t)(t) * 64 * 1024); kr1 = *(const v4u*)(kg + (size_t)(t) * 64 * 1024 + 32 * 1024); } while (0)
; #define AT_LOADV(t) do { vr0 = *(const v4u*)(vg + (t) * 64); vr1 = *(const v4u*)(vg + (size_t)64 * SEQ + (t) * 64); } while (0)
; #define AT_STOREK(bf) do { *(LAS v4u*)(lds + (bf) * AT_KBUF + kso) = kr0; *(LAS v4u*)(lds + (bf) * AT_KBUF + kso + 32 * AT_KSTR * 2) = kr1; } while (0)
; #define AT_STOREV(bf) do { *(LAS v2u*)(lds + (bf) * AT_VBUF + vso) = (v2u){vr0.x, vr0.y}; *(LAS v2u*)(lds + (bf) * AT_VBUF + vso + 8) = (v2u){vr0.z, vr0.w}; \
;         *(LAS v2u*)(lds + (bf) * AT_VBUF + vso + 64 * AT_VSTR * 2) = (v2u){vr1.x, vr1.y}; *(LAS v2u*)(lds + (bf) * AT_VBUF + vso + 64 * AT_VSTR * 2 + 8) = (v2u){vr1.z, vr1.w}; } while (0)
;     ...
;         const int qb = ui == 0 ? g16 : (ui == 1 ? 31 - g16 : (ui == 2 ? 32 + g16 : 63 - g16));
;         const int qw = qb * 128 + 32 * g, NT = 2 * qb + 2, qabs = qw + r;
;         const bf16* qp = Qd + ((size_t)(b * SEQ + qabs)) * 1024 + h * 128 + 64 * mi + 8 * hh;
;         bf16x8_t qf[4];
; #pragma unroll
;         for (int ds = 0; ds < 4; ++ds) qf[ds] = *(const bf16x8_t*)(qp + 16 * ds);
;         f32x16 o[4];
; #pragma unroll
;         for (int dt = 0; dt < 4; ++dt)
; #pragma unroll
;             for (int i = 0; i < 16; ++i) o[dt][i] = 0.f;
;         float mref = 0.f, l = 0.f; bool first = true;
;         v4u kr0, kr1, vr0, vr1;
;         const int NTw = (qw + 31) / 64 + 1 < NT ? (qw + 31) / 64 + 1 : NT;
;         const bool isY = wave >= 4;
;     ...
;         __syncthreads();
;         AT_LOADK(0); AT_LOADV(0); AT_STOREK(0); AT_STOREV(0); AT_LOADK(1); AT_STOREK(1);
;         __syncthreads();
;         if (isY) __syncthreads();
.LBB0_302:
	s_lshl_b32 s19, s4, 7
	s_add_i32 s18, s19, s42
	v_or_b32_e32 v49, s18, v218
	v_add_u32_e32 v212, s37, v49
	v_ashrrev_i32_e32 v213, 31, v212
	v_lshlrev_b64 v[0:1], 11, v[212:213]
	v_lshl_add_u64 v[0:1], v[180:181], 0, v[0:1]
	global_load_dwordx4 v[144:147], v[0:1], off
	global_load_dwordx4 v[148:151], v[0:1], off offset:32
	global_load_dwordx4 v[152:155], v[0:1], off offset:64
	global_load_dwordx4 v[156:159], v[0:1], off offset:96
	s_waitcnt lgkmcnt(0)
	s_barrier
	global_load_dwordx4 v[0:3], v[176:177], off
	global_load_dwordx4 v[4:7], v[182:183], off
	global_load_dwordx4 v[8:11], v[178:179], off
	global_load_dwordx4 v[12:15], v[184:185], off
	global_load_dwordx4 v[160:163], v[186:187], off
	global_load_dwordx4 v[164:167], v[188:189], off
	s_andn2_b64 vcc, exec, s[24:25]
	s_waitcnt vmcnt(5)
	ds_write_b128 v219, v[0:3]
	s_waitcnt vmcnt(4)
	ds_write_b128 v219, v[4:7] offset:8704
	v_add_u32_e32 v0, 0x8800, v220
	s_waitcnt vmcnt(3)
	ds_write2_b64 v0, v[8:9], v[10:11] offset1:2
	v_add_u32_e32 v0, 0xac00, v220
	s_waitcnt vmcnt(2)
	ds_write2_b64 v0, v[12:13], v[14:15] offset1:2
	s_waitcnt vmcnt(1)
	ds_write_b128 v219, v[160:163] offset:17408
	s_waitcnt vmcnt(0)
	ds_write_b128 v219, v[164:167] offset:26112
	s_waitcnt lgkmcnt(0)
	s_barrier
	s_cbranch_vccnz .LBB0_304
	s_barrier

.LBB0_386:
	v_max3_f32 v33, v16, v17, v0
	v_max3_f32 v34, v18, v19, v1
	s_cmp_eq_u64 exec, 0
	v_max3_f32 v33, v33, v2, v3
	v_max3_f32 v34, v34, v22, v23
	s_cselect_b64 s[40:41], -1, 0
	v_max3_f32 v33, v33, v20, v21
	v_max3_f32 v34, v34, v6, v7
	v_add_u32_e32 v46, 0x9900, v223
	v_max3_f32 v33, v33, v4, v5
	v_max3_f32 v34, v34, v26, v27
	s_nop 0
	v_max3_f32 v33, v33, v24, v25
	v_max3_f32 v34, v34, v10, v11
	s_nop 0
	v_max3_f32 v33, v33, v8, v9
	v_max3_f32 v34, v34, v30, v31
	s_nop 0
	v_max3_f32 v33, v33, v28, v29
	v_max3_f32 v34, v34, v14, v15
	s_nop 0
	v_max3_f32 v33, v33, v12, v13
	v_max_f32_e32 v34, v34, v34
	v_max_f32_e32 v33, v33, v33
	v_max_f32_e32 v33, v33, v34
	v_mov_b32_e32 v34, v33
	s_nop 1
	v_permlane32_swap_b32_e32 v33, v34
	v_max_f32_e32 v34, v34, v34
	v_max_f32_e32 v33, v33, v33
	v_max_f32_e32 v33, v33, v34
	v_add_f32_e32 v33, 0, v33
	v_cndmask_b32_e64 v214, v33, 0, s[40:41]
	v_sub_f32_e32 v16, v16, v214
	v_sub_f32_e32 v17, v17, v214
	v_sub_f32_e32 v0, v0, v214
	v_sub_f32_e32 v1, v1, v214
	v_exp_f32_e32 v16, v16
	v_exp_f32_e32 v17, v17
	v_exp_f32_e32 v38, v0
	v_exp_f32_e32 v39, v1
	v_sub_f32_e32 v18, v18, v214
	v_sub_f32_e32 v19, v19, v214
	v_sub_f32_e32 v2, v2, v214
	v_sub_f32_e32 v3, v3, v214
	v_exp_f32_e32 v18, v18
	v_exp_f32_e32 v19, v19
	v_exp_f32_e32 v40, v2
	v_exp_f32_e32 v41, v3
	v_sub_f32_e32 v2, v20, v214
	v_sub_f32_e32 v3, v21, v214
	v_add_f32_e32 v0, 0, v16
	v_add_f32_e32 v1, 0, v17
	v_sub_f32_e32 v4, v4, v214
	v_sub_f32_e32 v5, v5, v214
	v_exp_f32_e32 v2, v2
	v_exp_f32_e32 v3, v3
	v_add_f32_e32 v0, v38, v0
	v_add_f32_e32 v1, v39, v1
	v_exp_f32_e32 v4, v4
	v_exp_f32_e32 v5, v5
	v_sub_f32_e32 v20, v22, v214
	v_sub_f32_e32 v21, v23, v214
	v_add_f32_e32 v0, v18, v0
	v_add_f32_e32 v1, v19, v1
	v_sub_f32_e32 v6, v6, v214
	v_sub_f32_e32 v7, v7, v214
	v_exp_f32_e32 v20, v20
	v_exp_f32_e32 v21, v21
	v_add_f32_e32 v0, v40, v0
	v_add_f32_e32 v1, v41, v1
	v_exp_f32_e32 v6, v6
	v_exp_f32_e32 v7, v7
	v_sub_f32_e32 v22, v24, v214
	v_sub_f32_e32 v23, v25, v214
	v_add_f32_e32 v0, v2, v0
	v_add_f32_e32 v1, v3, v1
	v_sub_f32_e32 v8, v8, v214
	v_sub_f32_e32 v9, v9, v214
	v_exp_f32_e32 v22, v22
	v_exp_f32_e32 v23, v23
	v_add_f32_e32 v0, v4, v0
	v_add_f32_e32 v1, v5, v1
	v_exp_f32_e32 v8, v8
	v_exp_f32_e32 v9, v9
	v_sub_f32_e32 v24, v26, v214
	v_sub_f32_e32 v25, v27, v214
	v_add_f32_e32 v0, v20, v0
	v_add_f32_e32 v1, v21, v1
	v_sub_f32_e32 v10, v10, v214
	v_sub_f32_e32 v11, v11, v214
	v_exp_f32_e32 v24, v24
	v_exp_f32_e32 v25, v25
	v_add_f32_e32 v0, v6, v0
	v_add_f32_e32 v1, v7, v1
	v_exp_f32_e32 v10, v10
	v_exp_f32_e32 v11, v11
	v_sub_f32_e32 v26, v28, v214
	v_sub_f32_e32 v27, v29, v214
	v_add_f32_e32 v0, v22, v0
	v_add_f32_e32 v1, v23, v1
	v_sub_f32_e32 v12, v12, v214
	v_sub_f32_e32 v13, v13, v214
	v_exp_f32_e32 v26, v26
	v_exp_f32_e32 v27, v27
	v_add_f32_e32 v0, v8, v0
	v_add_f32_e32 v1, v9, v1
	v_exp_f32_e32 v12, v12
	v_exp_f32_e32 v13, v13
	v_add_f32_e32 v0, v24, v0
	v_add_f32_e32 v1, v25, v1
	v_sub_f32_e32 v14, v14, v214
	v_sub_f32_e32 v15, v15, v214
	v_add_f32_e32 v0, v10, v0
	v_add_f32_e32 v1, v11, v1
	v_exp_f32_e32 v14, v14
	v_add_f32_e32 v0, v26, v0
	v_add_f32_e32 v1, v27, v1
	v_exp_f32_e32 v15, v15
	v_add_f32_e32 v28, v12, v0
	v_add_f32_e32 v29, v13, v1
	v_sub_f32_e32 v0, v30, v214
	v_sub_f32_e32 v1, v31, v214
	v_add_u32_e32 v33, 0x8800, v223
	v_exp_f32_e32 v30, v0
	v_exp_f32_e32 v31, v1
	v_cvt_pk_bf16_f32 v0, v16, v17
	v_cvt_pk_bf16_f32 v1, v18, v19
	v_cvt_pk_bf16_f32 v2, v2, v3
	v_cvt_pk_bf16_f32 v3, v20, v21
	v_cvt_pk_bf16_f32 v34, v22, v23
	v_cvt_pk_bf16_f32 v35, v24, v25
	v_cvt_pk_bf16_f32 v36, v26, v27
	v_cvt_pk_bf16_f32 v37, v30, v31
	v_cvt_pk_bf16_f32 v38, v38, v39
	v_cvt_pk_bf16_f32 v39, v40, v41
	v_cvt_pk_bf16_f32 v40, v4, v5
	v_cvt_pk_bf16_f32 v41, v6, v7
	v_cvt_pk_bf16_f32 v42, v8, v9
	v_cvt_pk_bf16_f32 v43, v10, v11
	v_cvt_pk_bf16_f32 v44, v12, v13
	v_cvt_pk_bf16_f32 v45, v14, v15
	s_setprio 0
	s_barrier
	ds_read_b128 v[4:7], v33
	ds_read_b128 v[8:11], v46 offset:256
	v_add_f32_e32 v12, v30, v28
	v_add_f32_e32 v13, v31, v29
	s_nop 0
	v_add_f32_e32 v12, v14, v12
	v_add_f32_e32 v13, v15, v13
	s_nop 0
	v_add_f32_e32 v12, v12, v13
	v_add_f32_e32 v250, 0, v12
	v_add_u32_e32 v47, 0xaa00, v223
	ds_read_b128 v[12:15], v47 offset:512
	v_add_u32_e32 v104, 0xbb00, v223
	ds_read_b128 v[80:83], v104 offset:768
	ds_read_b128 v[84:87], v33 offset:32
	ds_read_b128 v[88:91], v46 offset:288
	s_waitcnt lgkmcnt(5)
	v_mfma_f32_32x32x16_bf16 v[64:79], v[4:7], v[0:3], 0
	s_waitcnt lgkmcnt(4)
	v_mfma_f32_32x32x16_bf16 v[48:63], v[8:11], v[0:3], 0
	ds_read_b128 v[92:95], v47 offset:544
	ds_read_b128 v[96:99], v104 offset:800
	s_waitcnt lgkmcnt(5)
	v_mfma_f32_32x32x16_bf16 v[16:31], v[12:15], v[0:3], 0
	s_waitcnt lgkmcnt(4)
	v_mfma_f32_32x32x16_bf16 v[0:15], v[80:83], v[0:3], 0
	ds_read_b128 v[80:83], v33 offset:64
	ds_read_b128 v[100:103], v46 offset:320
	s_waitcnt lgkmcnt(5)
	v_mfma_f32_32x32x16_bf16 v[64:79], v[84:87], v[34:37], v[64:79]
	s_waitcnt lgkmcnt(4)
	v_mfma_f32_32x32x16_bf16 v[48:63], v[88:91], v[34:37], v[48:63]
	ds_read_b128 v[84:87], v47 offset:576
	ds_read_b128 v[88:91], v104 offset:832
	s_waitcnt lgkmcnt(5)
	v_mfma_f32_32x32x16_bf16 v[16:31], v[92:95], v[34:37], v[16:31]
	s_waitcnt lgkmcnt(4)
	v_mfma_f32_32x32x16_bf16 v[0:15], v[96:99], v[34:37], v[0:15]
	ds_read_b128 v[34:37], v33 offset:96
	ds_read_b128 v[92:95], v46 offset:352
	s_waitcnt lgkmcnt(5)
	v_mfma_f32_32x32x16_bf16 v[64:79], v[80:83], v[38:41], v[64:79]
	s_waitcnt lgkmcnt(4)
	v_mfma_f32_32x32x16_bf16 v[48:63], v[100:103], v[38:41], v[48:63]
	ds_read_b128 v[80:83], v47 offset:608
	ds_read_b128 v[96:99], v104 offset:864
	s_waitcnt lgkmcnt(5)
	v_mfma_f32_32x32x16_bf16 v[16:31], v[84:87], v[38:41], v[16:31]
	s_waitcnt lgkmcnt(4)
	v_mfma_f32_32x32x16_bf16 v[0:15], v[88:91], v[38:41], v[0:15]
	s_waitcnt lgkmcnt(3)
	v_mfma_f32_32x32x16_bf16 v[64:79], v[34:37], v[42:45], v[64:79]
	s_waitcnt lgkmcnt(2)
	v_mfma_f32_32x32x16_bf16 v[48:63], v[92:95], v[42:45], v[48:63]
	s_waitcnt lgkmcnt(1)
	v_mfma_f32_32x32x16_bf16 v[16:31], v[80:83], v[42:45], v[16:31]
	s_waitcnt lgkmcnt(0)
	v_mfma_f32_32x32x16_bf16 v[0:15], v[96:99], v[42:45], v[0:15]
	s_branch .LBB0_388

; #define AT_LOADK(t) do { kr0 = *(const v4u*)(kg + (size_t)(t) * 64 * 1024); kr1 = *(const v4u*)(kg + (size_t)(t) * 64 * 1024 + 32 * 1024); } while (0)
; #define AT_LOADV(t) do { vr0 = *(const v4u*)(vg + (t) * 64); vr1 = *(const v4u*)(vg + (size_t)64 * SEQ + (t) * 64); } while (0)
; #define AT_STOREK(bf) do { *(LAS v4u*)(lds + (bf) * AT_KBUF + kso) = kr0; *(LAS v4u*)(lds + (bf) * AT_KBUF + kso + 32 * AT_KSTR * 2) = kr1; } while (0)
; #define AT_STOREV(bf) do { *(LAS v2u*)(lds + (bf) * AT_VBUF + vso) = (v2u){vr0.x, vr0.y}; *(LAS v2u*)(lds + (bf) * AT_VBUF + vso + 8) = (v2u){vr0.z, vr0.w}; \
;         *(LAS v2u*)(lds + (bf) * AT_VBUF + vso + 64 * AT_VSTR * 2) = (v2u){vr1.x, vr1.y}; *(LAS v2u*)(lds + (bf) * AT_VBUF + vso + 64 * AT_VSTR * 2 + 8) = (v2u){vr1.z, vr1.w}; } while (0)
;     ...
;         __syncthreads();
;         AT_LOADK(0); AT_LOADV(0); AT_STOREK(0); AT_STOREV(0); AT_LOADK(1); AT_STOREK(1);
;         __syncthreads();
;         if (isY) __syncthreads();
;         for (int t = 0; t < NT; ++t) {
;             f32x16 p0, p1; bf16x8_t pb0, pb1, pb2, pb3;
; #pragma unroll
;             for (int i = 0; i < 16; ++i) { p0[i] = 0.f; p1[i] = 0.f; }
;             if (t < NTw) AT_QKB(t & 1);
;             if (!(AMODE & 4) && t >= 1) { if (t + 1 < NT) AT_STOREK((t + 1) & 1); if (t < NT) AT_STOREV(t & 1); }
;             __syncthreads();
;             if (!(AMODE & 4)) { if (t + 2 < NT) AT_LOADK(t + 2); if (t + 1 < NT) AT_LOADV(t + 1); }
;             if (t < NTw) {
;                 AT_SOFTMAX(t);
;                 __syncthreads();
;                 AT_PVB(t & 1);
.LBB0_468:
	v_sub_f32_e32 v34, v96, v214
	v_sub_f32_e32 v35, v97, v214
	v_sub_f32_e32 v36, v80, v214
	v_sub_f32_e32 v37, v81, v214
	v_exp_f32_e32 v34, v34
	v_exp_f32_e32 v35, v35
	v_exp_f32_e32 v42, v36
	v_exp_f32_e32 v43, v37
	v_lshl_add_u64 v[252:253], s[94:95], 1, v[178:179]
	global_load_dwordx4 v[168:171], v[252:253], off
	v_sub_f32_e32 v38, v98, v214
	v_sub_f32_e32 v39, v99, v214
	v_sub_f32_e32 v40, v82, v214
	v_sub_f32_e32 v41, v83, v214
	v_exp_f32_e32 v38, v38
	v_exp_f32_e32 v39, v39
	v_exp_f32_e32 v44, v40
	v_exp_f32_e32 v45, v41
	v_sub_f32_e32 v40, v100, v214
	v_sub_f32_e32 v41, v101, v214
	v_add_f32_e32 v36, 0, v34
	v_add_f32_e32 v37, 0, v35
	v_sub_f32_e32 v46, v84, v214
	v_sub_f32_e32 v47, v85, v214
	v_exp_f32_e32 v40, v40
	v_exp_f32_e32 v41, v41
	v_add_f32_e32 v36, v42, v36
	v_add_f32_e32 v37, v43, v37
	v_exp_f32_e32 v46, v46
	v_exp_f32_e32 v47, v47
	v_sub_f32_e32 v80, v102, v214
	v_sub_f32_e32 v81, v103, v214
	v_add_f32_e32 v36, v38, v36
	v_add_f32_e32 v37, v39, v37
	v_sub_f32_e32 v82, v86, v214
	v_sub_f32_e32 v83, v87, v214
	v_exp_f32_e32 v80, v80
	v_exp_f32_e32 v81, v81
	v_add_f32_e32 v36, v44, v36
	v_add_f32_e32 v37, v45, v37
	v_exp_f32_e32 v82, v82
	v_exp_f32_e32 v83, v83
	v_lshl_add_u64 v[252:253], s[94:95], 1, v[184:185]
	global_load_dwordx4 v[172:175], v[252:253], off
	v_sub_f32_e32 v84, v104, v214
	v_sub_f32_e32 v85, v105, v214
	v_add_f32_e32 v36, v40, v36
	v_add_f32_e32 v37, v41, v37
	v_sub_f32_e32 v86, v88, v214
	v_sub_f32_e32 v87, v89, v214
	v_exp_f32_e32 v84, v84
	v_exp_f32_e32 v85, v85
	v_add_f32_e32 v36, v46, v36
	v_add_f32_e32 v37, v47, v37
	v_exp_f32_e32 v86, v86
	v_exp_f32_e32 v87, v87
	v_sub_f32_e32 v88, v106, v214
	v_sub_f32_e32 v89, v107, v214
	v_add_f32_e32 v36, v80, v36
	v_add_f32_e32 v37, v81, v37
	v_sub_f32_e32 v90, v90, v214
	v_sub_f32_e32 v91, v91, v214
	v_exp_f32_e32 v88, v88
	v_exp_f32_e32 v89, v89
	v_add_f32_e32 v36, v82, v36
	v_add_f32_e32 v37, v83, v37
	v_exp_f32_e32 v90, v90
	v_exp_f32_e32 v91, v91
	v_sub_f32_e32 v96, v108, v214
	v_sub_f32_e32 v97, v109, v214
	v_add_f32_e32 v36, v84, v36
	v_add_f32_e32 v37, v85, v37
	v_sub_f32_e32 v92, v92, v214
	v_sub_f32_e32 v93, v93, v214
	v_exp_f32_e32 v96, v96
	v_exp_f32_e32 v97, v97
	v_add_f32_e32 v36, v86, v36
	v_add_f32_e32 v37, v87, v37
	v_exp_f32_e32 v92, v92
	v_exp_f32_e32 v93, v93
	v_add_f32_e32 v36, v88, v36
	v_add_f32_e32 v37, v89, v37
	v_sub_f32_e32 v94, v94, v214
	v_sub_f32_e32 v95, v95, v214
	v_add_f32_e32 v36, v90, v36
	v_add_f32_e32 v37, v91, v37
	v_exp_f32_e32 v94, v94
	v_add_f32_e32 v36, v96, v36
	v_add_f32_e32 v37, v97, v37
	v_exp_f32_e32 v95, v95
	v_add_f32_e32 v98, v92, v36
	v_add_f32_e32 v99, v93, v37
	v_sub_f32_e32 v36, v110, v214
	v_sub_f32_e32 v37, v111, v214
	v_add_u32_e32 v33, s49, v223
	v_exp_f32_e32 v100, v36
	v_exp_f32_e32 v101, v37
	v_add_u32_e32 v108, 0x8800, v33
	v_add_u32_e32 v109, 0x9900, v33
	v_cvt_pk_bf16_f32 v34, v34, v35
	v_cvt_pk_bf16_f32 v35, v38, v39
	v_cvt_pk_bf16_f32 v36, v40, v41
	v_cvt_pk_bf16_f32 v37, v80, v81
	v_cvt_pk_bf16_f32 v38, v84, v85
	v_cvt_pk_bf16_f32 v39, v88, v89
	v_cvt_pk_bf16_f32 v40, v96, v97
	v_cvt_pk_bf16_f32 v41, v100, v101
	v_cvt_pk_bf16_f32 v42, v42, v43
	v_cvt_pk_bf16_f32 v43, v44, v45
	v_cvt_pk_bf16_f32 v44, v46, v47
	v_cvt_pk_bf16_f32 v45, v82, v83
	v_cvt_pk_bf16_f32 v80, v86, v87
	v_cvt_pk_bf16_f32 v81, v90, v91
	v_cvt_pk_bf16_f32 v82, v92, v93
	v_cvt_pk_bf16_f32 v83, v94, v95
	s_setprio 0
	s_barrier
	ds_read_b128 v[84:87], v108
	ds_read_b128 v[88:91], v109 offset:256
	v_add_f32_e32 v46, v100, v98
	v_add_f32_e32 v47, v101, v99
	s_nop 0
	v_add_f32_e32 v46, v94, v46
	v_add_f32_e32 v47, v95, v47
	s_nop 0
	v_add_f32_e32 v46, v46, v47
	v_add_f32_e32 v250, v250, v46
	v_add_u32_e32 v46, 0xaa00, v33
	v_add_u32_e32 v33, 0xbb00, v33
	ds_read_b128 v[92:95], v46 offset:512
	ds_read_b128 v[96:99], v33 offset:768
	ds_read_b128 v[100:103], v108 offset:32
	ds_read_b128 v[104:107], v109 offset:288
	s_waitcnt lgkmcnt(5)
	v_mfma_f32_32x32x16_bf16 v[64:79], v[84:87], v[34:37], v[64:79]
	s_waitcnt lgkmcnt(4)
	v_mfma_f32_32x32x16_bf16 v[48:63], v[88:91], v[34:37], v[48:63]
	ds_read_b128 v[84:87], v46 offset:544
	ds_read_b128 v[88:91], v33 offset:800
	s_waitcnt lgkmcnt(5)
	v_mfma_f32_32x32x16_bf16 v[16:31], v[92:95], v[34:37], v[16:31]
	s_waitcnt lgkmcnt(4)
	v_mfma_f32_32x32x16_bf16 v[0:15], v[96:99], v[34:37], v[0:15]
	ds_read_b128 v[34:37], v108 offset:64
	ds_read_b128 v[92:95], v109 offset:320
	s_waitcnt lgkmcnt(5)
	v_mfma_f32_32x32x16_bf16 v[64:79], v[100:103], v[38:41], v[64:79]
	s_waitcnt lgkmcnt(4)
	v_mfma_f32_32x32x16_bf16 v[48:63], v[104:107], v[38:41], v[48:63]
	ds_read_b128 v[96:99], v46 offset:576
	ds_read_b128 v[100:103], v33 offset:832
	s_waitcnt lgkmcnt(5)
	v_mfma_f32_32x32x16_bf16 v[16:31], v[84:87], v[38:41], v[16:31]
	s_waitcnt lgkmcnt(4)
	v_mfma_f32_32x32x16_bf16 v[0:15], v[88:91], v[38:41], v[0:15]
	ds_read_b128 v[38:41], v108 offset:96
	ds_read_b128 v[84:87], v109 offset:352
	s_waitcnt lgkmcnt(5)
	v_mfma_f32_32x32x16_bf16 v[64:79], v[34:37], v[42:45], v[64:79]
	s_waitcnt lgkmcnt(4)
	v_mfma_f32_32x32x16_bf16 v[48:63], v[92:95], v[42:45], v[48:63]
	ds_read_b128 v[34:37], v46 offset:608
	ds_read_b128 v[88:91], v33 offset:864
	s_waitcnt lgkmcnt(5)
	v_mfma_f32_32x32x16_bf16 v[16:31], v[96:99], v[42:45], v[16:31]
	s_waitcnt lgkmcnt(4)
	v_mfma_f32_32x32x16_bf16 v[0:15], v[100:103], v[42:45], v[0:15]
	s_waitcnt lgkmcnt(3)
	v_mfma_f32_32x32x16_bf16 v[64:79], v[38:41], v[80:83], v[64:79]
	s_waitcnt lgkmcnt(2)
	v_mfma_f32_32x32x16_bf16 v[48:63], v[84:87], v[80:83], v[48:63]
	s_waitcnt lgkmcnt(1)
	v_mfma_f32_32x32x16_bf16 v[16:31], v[34:37], v[80:83], v[16:31]
	s_waitcnt lgkmcnt(0)
	v_mfma_f32_32x32x16_bf16 v[0:15], v[88:91], v[80:83], v[0:15]
